# diff-attn loop: static s_setprio 1 for waves 0-3 instead of 4-7
# baseline (speedup 1.0000x reference)
; #define SBAR() __builtin_amdgcn_sched_barrier(0)
; #define VMW() asm volatile("s_waitcnt vmcnt(0)" ::: "memory")
; #define SLOAD_H(Kp, Vp, k0) do { S.st_v0 = load8<TIn>(ROW(Vp, k0, sr)); S.st_v1 = load8<TIn>(ROW(Vp, k0, 32 + sr));              \
;                          S.st_k0 = load8<TIn>(ROW(Kp, k0, sr)); S.st_k1 = load8<TIn>(ROW(Kp, k0, 32 + sr)); } while (0)
; #define SWRITE_HV(bf) do { *(bf16x8*)(V_lds + (bf) * SHM_V + vst0) = S.st_v0; *(bf16x8*)(V_lds + (bf) * SHM_V + vst1) = S.st_v1; } while (0)
; #define SWRITE_H(bf) do { SWRITE_HV(bf); SWRITE_HK(bf); } while (0)
; #define SLOAD_F(p, k0) do { S.sf0 = *(const f32x4*)ROW(p, k0, sr); S.sf1 = *(const f32x4*)(ROW(p, k0, sr) + 4);                \
;                             S.sf2 = *(const f32x4*)ROW(p, k0, 32 + sr); S.sf3 = *(const f32x4*)(ROW(p, k0, 32 + sr) + 4); } while (0)
; #define SWRITE_KF(bf) do { *(bf16x8*)(K_lds + (bf) * SHM_K + kws) = pack8(S.sf0, S.sf1); *(bf16x8*)(K_lds + (bf) * SHM_K + kws + 32 * 256) = pack8(S.sf2, S.sf3); } while (0)
; #define SWRITE_VF(bf) do { *(bf16x8*)(V_lds + (bf) * SHM_V + vst0) = pack8(S.sf0, S.sf1); *(bf16x8*)(V_lds + (bf) * SHM_V + vst1) = pack8(S.sf2, S.sf3); } while (0)
; #define ACT(t) (KBASE(t) <= qlo + QBLK - 1 && KBASE(t) + KVBLK - 1 >= qlo - W + 1)
; #define MASKT(P0_, P1_, t) do { const int kb_ = KBASE(t); if ((!SK || ACT(t)) && (kb_ + KVBLK - 1 > qlo || kb_ <= qlo + QBLK - 1 - W)) mask_tile(P0_, P1_, qm - kb_, (unsigned)W); } while (0)
; template <class TIn, class TOut>
; __device__ __forceinline__ void causal_swa_block(const BlockRef<TIn, TOut>& cur, const BlockRef<TIn, TOut>& nxt, int skv, int W, char* lds, Seam<TIn>& S) {
;     ...
;     if constexpr (F32) { VMW(); SWRITE_VF(0); SBAR(); } else { SWRITE_HV(0); SBAR(); }
;     if (NT > 1) { if constexpr (F32) SLOAD_F((const float*)Kh, KBASE(1)); else SLOAD_H(Kh, Vh, KBASE(1)); }
;     SBAR(); qkt<0, SK>(pA0, pA1, K_lds, r32, hi, S.qr, ACT(0));
;     if constexpr (F32) { if (NT > 1) { VMW(); SWRITE_KF(1); SBAR(); SLOAD_F((const float*)Vh, KBASE(1)); } }
;     MASKT(pA0, pA1, 0); partialSM(pA0, pA1, m_reg, mnA, alA);
;     if (NT > 1) { VMW(); if constexpr (F32) { SWRITE_VF(1); SBAR(); if (NT > 2) SLOAD_F((const float*)Kh, KBASE(2)); } else SWRITE_H(1); }
;     __syncthreads();
.LBB0_1128:
	s_nop 8
	v_max_f32_e32 v50, v19, v19
	v_max_f32_e32 v51, v18, v18
	v_max_f32_e32 v50, v51, v50
	v_max3_f32 v50, v50, v20, v21
	v_max3_f32 v50, v50, v22, v23
	v_max3_f32 v50, v50, v24, v25
	v_max3_f32 v50, v50, v26, v27
	v_max3_f32 v50, v50, v28, v29
	v_max3_f32 v50, v50, v30, v31
	v_max3_f32 v50, v50, v32, v33
	v_max3_f32 v50, v50, v2, v3
	v_max3_f32 v50, v50, v4, v5
	v_max3_f32 v50, v50, v6, v7
	v_max3_f32 v50, v50, v8, v9
	v_max3_f32 v50, v50, v10, v11
	v_max3_f32 v50, v50, v12, v13
	v_max3_f32 v50, v50, v14, v15
	v_max3_f32 v50, v50, v16, v17
	v_mov_b32_e32 v51, v50
	s_nop 1
	v_permlane32_swap_b32_e32 v50, v51
	v_max_f32_e32 v51, v51, v51
	v_max_f32_e32 v50, v50, v50
	v_max_f32_e32 v50, v50, v51
	s_and_b32 s4, s4, 0x3fffffc0
	v_add_f32_e32 v51, 0x7149f2ca, v50
	s_lshl_b32 s4, s4, 2
	v_mul_f32_e32 v51, 0x3db504f3, v51
	v_max_f32_e32 v50, 0xf149f2ca, v50
	s_add_i32 s14, s80, 0xff
	s_add_i32 s4, s4, 0
	v_cmp_ge_f32_e32 vcc, s86, v51
	v_sub_f32_e32 v51, 0xf149f2ca, v50
	s_lshr_b32 s24, s14, 6
	s_add_i32 s4, s4, 0x10000
	s_add_i32 s15, s13, 0xffffc01f
	v_mul_f32_e32 v51, 0x3e0293ee, v51
	v_exp_f32_e32 v51, v51
	s_cmp_eq_u64 vcc, exec
	s_cselect_b64 vcc, -1, 0
	v_cndmask_b32_e32 v178, v50, v216, vcc
	v_mul_f32_e32 v50, 0xbe0293ee, v178
	v_cndmask_b32_e64 v197, v51, 1.0, vcc
	v_mov_b32_e32 v51, v50
	v_fmamk_f32 v18, v18, 0x3e0293ee, v50
	v_fmamk_f32 v19, v19, 0x3e0293ee, v50
	v_fmamk_f32 v20, v20, 0x3e0293ee, v50
	v_fmamk_f32 v21, v21, 0x3e0293ee, v50
	v_fmamk_f32 v22, v22, 0x3e0293ee, v50
	v_fmamk_f32 v23, v23, 0x3e0293ee, v50
	v_fmamk_f32 v24, v24, 0x3e0293ee, v50
	v_fmamk_f32 v25, v25, 0x3e0293ee, v50
	v_fmamk_f32 v26, v26, 0x3e0293ee, v50
	v_fmamk_f32 v27, v27, 0x3e0293ee, v50
	v_fmamk_f32 v28, v28, 0x3e0293ee, v50
	v_fmamk_f32 v29, v29, 0x3e0293ee, v50
	v_fmamk_f32 v30, v30, 0x3e0293ee, v50
	v_fmamk_f32 v31, v31, 0x3e0293ee, v50
	v_fmamk_f32 v32, v32, 0x3e0293ee, v50
	v_fmac_f32_e32 v51, 0x3e0293ee, v33
	v_exp_f32_e32 v170, v18
	v_exp_f32_e32 v171, v19
	v_exp_f32_e32 v172, v20
	v_exp_f32_e32 v173, v21
	v_exp_f32_e32 v174, v22
	v_exp_f32_e32 v176, v23
	v_exp_f32_e32 v175, v24
	v_exp_f32_e32 v177, v25
	v_exp_f32_e32 v162, v26
	v_exp_f32_e32 v163, v27
	v_exp_f32_e32 v164, v28
	v_exp_f32_e32 v166, v29
	v_exp_f32_e32 v165, v30
	v_exp_f32_e32 v167, v31
	v_exp_f32_e32 v168, v32
	v_exp_f32_e32 v169, v51
	s_waitcnt vmcnt(0)
	s_waitcnt vmcnt(3)
	ds_write_b128 v209, v[34:37] offset:16384
	s_waitcnt vmcnt(1)
	ds_write_b128 v210, v[46:49] offset:16384
	ds_write_b128 v217, v[38:41] offset:49152
	s_waitcnt vmcnt(0)
	ds_write_b128 v217, v[42:45] offset:57344
	v_mov_b32_e32 v34, v195
	v_mov_b32_e32 v35, v195
	v_mov_b32_e32 v48, v195
	v_mov_b32_e32 v49, v195
	v_pk_fma_f32 v[118:119], v[16:17], s[50:51], v[50:51] op_sel_hi:[1,0,0]
	v_pk_fma_f32 v[122:123], v[14:15], s[50:51], v[50:51] op_sel_hi:[1,0,0]
	v_pk_fma_f32 v[128:129], v[12:13], s[50:51], v[50:51] op_sel_hi:[1,0,0]
	v_pk_fma_f32 v[114:115], v[10:11], s[50:51], v[50:51] op_sel_hi:[1,0,0]
	v_pk_fma_f32 v[116:117], v[8:9], s[50:51], v[50:51] op_sel_hi:[1,0,0]
	v_pk_fma_f32 v[120:121], v[6:7], s[50:51], v[50:51] op_sel_hi:[1,0,0]
	v_pk_fma_f32 v[124:125], v[4:5], s[50:51], v[50:51] op_sel_hi:[1,0,0]
	v_pk_fma_f32 v[126:127], v[2:3], s[50:51], v[50:51] op_sel_hi:[1,0,0]
	v_mov_b32_e32 v36, v195
	v_mov_b32_e32 v37, v195
	v_mov_b32_e32 v38, v195
	v_mov_b32_e32 v39, v195
	v_mov_b32_e32 v40, v195
	v_mov_b32_e32 v41, v195
	v_mov_b32_e32 v42, v195
	v_mov_b32_e32 v43, v195
	v_mov_b32_e32 v44, v195
	v_mov_b32_e32 v45, v195
	v_mov_b32_e32 v46, v195
	v_mov_b32_e32 v47, v195
	v_mov_b64_e32 v[64:65], v[48:49]
	v_mov_b64_e32 v[18:19], v[34:35]
	v_mov_b64_e32 v[2:3], v[34:35]
	s_mov_b32 s25, 2
	v_lshl_add_u32 v219, v199, 2, s4
	v_lshl_add_u32 v218, v200, 2, s4
	v_add_u32_e32 v222, s12, v201
	v_mov_b32_e32 v221, 0
	s_movk_i32 s26, 0xbf
	v_mov_b32_e32 v194, v203
	v_mov_b64_e32 v[62:63], v[46:47]
	v_mov_b64_e32 v[60:61], v[44:45]
	v_mov_b64_e32 v[58:59], v[42:43]
	v_mov_b64_e32 v[56:57], v[40:41]
	v_mov_b64_e32 v[54:55], v[38:39]
	v_mov_b64_e32 v[52:53], v[36:37]
	v_mov_b64_e32 v[50:51], v[34:35]
	v_mov_b64_e32 v[20:21], v[36:37]
	v_mov_b64_e32 v[22:23], v[38:39]
	v_mov_b64_e32 v[24:25], v[40:41]
	v_mov_b64_e32 v[26:27], v[42:43]
	v_mov_b64_e32 v[28:29], v[44:45]
	v_mov_b64_e32 v[30:31], v[46:47]
	v_mov_b64_e32 v[32:33], v[48:49]
	v_mov_b64_e32 v[4:5], v[36:37]
	v_mov_b64_e32 v[6:7], v[38:39]
	v_mov_b64_e32 v[8:9], v[40:41]
	v_mov_b64_e32 v[10:11], v[42:43]
	v_mov_b64_e32 v[12:13], v[44:45]
	v_mov_b64_e32 v[14:15], v[46:47]
	v_mov_b64_e32 v[16:17], v[48:49]
	s_waitcnt lgkmcnt(0)
	s_barrier
	v_lshlrev_b32_e32 v255, 1, v194
	v_mov_b32_e32 v252, v178
	v_mul_f32_e32 v253, 0xbe0293ee, v178
	v_readfirstlane_b32 s52, v1
	s_nop 3
	s_and_b32 s52, s52, 0x3ff
	s_cmpk_ge_u32 s52, 0x100
	s_cbranch_scc1 .Lattn_prio_skip
	s_setprio 1
